# attention unit epilogue: sub-LN gain loads issued at the top of the normalisation block (free registers) so their latency is covered; stacked on stack23
# speedup vs baseline: 1.0109x; 1.0002x over previous
; __device__ __forceinline__ int crow(int r, int hi) { return (r & 3) + 8 * (r >> 2) + 4 * hi; }
;     ...
;     if (hi == 0) { wsf[64 + r32] = 1.f / lA; wsf[96 + r32] = lam / lB; }
;     asm volatile("s_waitcnt lgkmcnt(0)" ::: "memory");
;     float* stg = (float*)(shm + LDS_OST) + wid * 2048;
; #pragma unroll
;     for (int r = 0; r < 16; ++r) { const int orow = crow(r, hi); const float a = wsf[64 + orow], c = wsf[96 + orow];
;         stg[orow * 64 + r32] = oa0[r] * a - ob0[r] * c; stg[orow * 64 + 32 + r32] = oa1[r] * a - ob1[r] * c; }
;     asm volatile("s_waitcnt lgkmcnt(0)" ::: "memory");
;     bf16_t* Ow = mix + (rowbase + q0 + wid * 32) * D + h * 64;
;     const int ch = lane & 7;
;     const float4 g0 = *(const float4*)(gsub + ch * 8), g1 = *(const float4*)(gsub + ch * 8 + 4);
; #pragma unroll
;     for (int i = 0; i < 4; ++i) { const int row = i * 8 + (lane >> 3);
;         const float4 a = *(const float4*)(stg + row * 64 + ch * 8), c = *(const float4*)(stg + row * 64 + ch * 8 + 4);
.LBB0_372:
	s_or_b64 exec, exec, s[36:37]
	s_add_u32 s17, s66, s96
	s_addc_u32 s18, s67, s97
	s_lshl_b64 s[14:15], s[70:71], 2
	s_add_u32 s14, s17, s14
	s_addc_u32 s15, s18, s15
	v_lshlrev_b32_e32 v108, 3, v168
	v_and_b32_e32 v108, 56, v108
	v_lshlrev_b32_e32 v108, 2, v108
	global_load_dwordx4 v[100:103], v108, s[14:15]
	global_load_dwordx4 v[104:107], v108, s[14:15] offset:16
	s_waitcnt lgkmcnt(0)
	ds_read_b32 v68, v185 offset:384
	ds_read_b32 v69, v185 offset:256
	ds_read_b32 v70, v185 offset:388
	ds_read_b32 v71, v185 offset:260
	ds_read_b32 v72, v185 offset:392
	ds_read_b32 v73, v185 offset:264
	ds_read_b32 v74, v185 offset:396
	ds_read_b32 v75, v185 offset:268
	ds_read_b32 v76, v185 offset:416
	ds_read_b32 v77, v185 offset:288
	ds_read_b32 v78, v185 offset:420
	ds_read_b32 v79, v185 offset:292
	ds_read_b32 v80, v185 offset:424
	ds_read_b32 v81, v185 offset:296
	ds_read_b32 v82, v185 offset:428
	ds_read_b32 v83, v185 offset:300
	ds_read_b32 v84, v185 offset:448
	ds_read_b32 v85, v185 offset:320
	ds_read_b32 v86, v185 offset:452
	ds_read_b32 v87, v185 offset:324
	ds_read_b32 v88, v185 offset:456
	ds_read_b32 v89, v185 offset:328
	ds_read_b32 v90, v185 offset:460
	ds_read_b32 v91, v185 offset:332
	ds_read_b32 v92, v185 offset:480
	ds_read_b32 v93, v185 offset:352
	ds_read_b32 v94, v185 offset:484
	ds_read_b32 v95, v185 offset:356
	ds_read_b32 v96, v185 offset:360
	ds_read_b32 v97, v185 offset:488
	ds_read_b32 v98, v185 offset:364
	ds_read_b32 v99, v185 offset:492
	s_waitcnt lgkmcnt(0)
	v_lshl_add_u32 v66, v170, 2, s25
	v_lshl_add_u32 v67, v169, 10, v66
	v_mul_f32_e32 v16, v16, v68
	v_mul_f32_e32 v0, v0, v68
	v_fma_f32 v16, v48, v69, -v16
	v_fma_f32 v0, v32, v69, -v0
	ds_write2_b32 v67, v16, v0 offset1:32
	v_lshl_add_u32 v32, v172, 8, v66
	v_mul_f32_e32 v17, v17, v70
	v_mul_f32_e32 v0, v1, v70
	v_fma_f32 v1, v49, v71, -v17
	v_fma_f32 v0, v33, v71, -v0
	ds_write2_b32 v32, v1, v0 offset0:64 offset1:96
	s_mov_b32 s8, 0x3c800000
	v_mul_f32_e32 v16, v18, v72
	v_mul_f32_e32 v0, v2, v72
	v_fma_f32 v2, v50, v73, -v16
	v_fma_f32 v0, v34, v73, -v0
	ds_write2_b32 v32, v2, v0 offset0:128 offset1:160
	s_mov_b64 s[38:39], 0x7200000
	s_mov_b64 s[36:37], 0
	v_mul_f32_e32 v2, v19, v74
	v_mul_f32_e32 v0, v3, v74
	v_fma_f32 v2, v51, v75, -v2
	v_fma_f32 v0, v35, v75, -v0
	ds_write2_b32 v32, v2, v0 offset0:192 offset1:224
	v_add_u32_e32 v2, 0x800, v32
	v_mul_f32_e32 v3, v20, v76
	v_mul_f32_e32 v0, v4, v76
	v_fma_f32 v3, v52, v77, -v3
	v_fma_f32 v0, v36, v77, -v0
	ds_write2_b32 v2, v3, v0 offset1:32
	v_mul_f32_e32 v3, v21, v78
	v_mul_f32_e32 v0, v5, v78
	v_fma_f32 v3, v53, v79, -v3
	v_fma_f32 v0, v37, v79, -v0
	ds_write2_b32 v2, v3, v0 offset0:64 offset1:96
	v_mul_f32_e32 v3, v22, v80
	v_mul_f32_e32 v0, v6, v80
	v_fma_f32 v3, v54, v81, -v3
	v_fma_f32 v0, v38, v81, -v0
	ds_write2_b32 v2, v3, v0 offset0:128 offset1:160
	v_mul_f32_e32 v3, v23, v82
	v_mul_f32_e32 v0, v7, v82
	v_fma_f32 v3, v55, v83, -v3
	v_fma_f32 v0, v39, v83, -v0
	ds_write2_b32 v2, v3, v0 offset0:192 offset1:224
	v_add_u32_e32 v2, 0x1000, v32
	v_mul_f32_e32 v3, v24, v84
	v_mul_f32_e32 v0, v8, v84
	v_fma_f32 v3, v56, v85, -v3
	v_fma_f32 v0, v40, v85, -v0
	ds_write2_b32 v2, v3, v0 offset1:32
	v_mul_f32_e32 v3, v25, v86
	v_mul_f32_e32 v0, v9, v86
	v_fma_f32 v3, v57, v87, -v3
	v_fma_f32 v0, v41, v87, -v0
	ds_write2_b32 v2, v3, v0 offset0:64 offset1:96
	v_mov_b64_e32 v[24:25], s[84:85]
	v_mul_f32_e32 v3, v26, v88
	v_mul_f32_e32 v0, v10, v88
	v_fma_f32 v3, v58, v89, -v3
	v_fma_f32 v0, v42, v89, -v0
	ds_write2_b32 v2, v3, v0 offset0:128 offset1:160
	v_mul_f32_e32 v3, v27, v90
	v_mul_f32_e32 v0, v11, v90
	v_fma_f32 v3, v59, v91, -v3
	v_fma_f32 v0, v43, v91, -v0
	ds_write2_b32 v2, v3, v0 offset0:192 offset1:224
	v_add_u32_e32 v2, 0x1800, v32
	v_mul_f32_e32 v3, v28, v92
	v_mul_f32_e32 v0, v12, v92
	v_fma_f32 v3, v60, v93, -v3
	v_fma_f32 v0, v44, v93, -v0
	ds_write2_b32 v2, v3, v0 offset1:32
	v_mul_f32_e32 v3, v29, v94
	v_mul_f32_e32 v0, v13, v94
	v_fma_f32 v3, v61, v95, -v3
	v_fma_f32 v0, v45, v95, -v0
	ds_write2_b32 v2, v3, v0 offset0:64 offset1:96
	v_lshlrev_b32_e32 v3, 3, v168
	v_and_b32_e32 v8, 56, v3
	v_lshlrev_b32_e32 v9, 2, v8
	v_add_u32_e32 v48, s25, v9
	v_mul_f32_e32 v4, v30, v97
	v_mul_f32_e32 v1, v14, v97
	v_fma_f32 v4, v62, v96, -v4
	v_fma_f32 v0, v46, v96, -v1
	ds_write2_b32 v2, v4, v0 offset0:128 offset1:160
	v_lshrrev_b32_e32 v46, 3, v167
	v_lshlrev_b32_e32 v128, 1, v8
	v_lshl_add_u32 v8, v46, 8, v48
	v_or_b32_e32 v52, 16, v46
	v_mul_f32_e32 v3, v31, v99
	v_mul_f32_e32 v1, v15, v99
	v_fma_f32 v3, v63, v98, -v3
	v_fma_f32 v0, v47, v98, -v1
	ds_write2_b32 v2, v3, v0 offset0:192 offset1:224
	s_waitcnt lgkmcnt(0)
	v_or_b32_e32 v47, 8, v46
	v_lshl_add_u32 v9, v47, 8, v48
	ds_read_b128 v[20:23], v8
	ds_read_b128 v[16:19], v8 offset:16
	ds_read_b128 v[12:15], v9
	ds_read_b128 v[8:11], v9 offset:16
	s_lshl_b64 s[14:15], s[50:51], 11
	s_add_u32 s14, s48, s14
	s_waitcnt lgkmcnt(3)
	v_pk_mul_f32 v[34:35], v[20:21], v[20:21]
	s_waitcnt lgkmcnt(1)
	v_pk_mul_f32 v[42:43], v[12:13], v[12:13]
	v_pk_mul_f32 v[32:33], v[22:23], v[22:23]
	v_pk_mul_f32 v[40:41], v[14:15], v[14:15]
	v_mov_b32_e32 v44, v42
	v_mov_b32_e32 v45, v34
	v_mov_b32_e32 v34, v43
	v_mov_b32_e32 v42, v40
	v_mov_b32_e32 v43, v32
	v_pk_add_f32 v[34:35], v[44:45], v[34:35]
	v_pk_mul_f32 v[30:31], v[16:17], v[16:17]
	s_waitcnt lgkmcnt(0)
; __device__ __forceinline__ unsigned cvtpk_s(float lo, float hi) { f32x2_t v = {lo, hi}; bf16x2_t b = __builtin_convertvector(v, bf16x2_t); return __builtin_bit_cast(unsigned, b); }
; __device__ __forceinline__ float sum8f(float x) { x += dppf<0xB1>(x); x += dppf<0x4E>(x); x += dppf<0x141>(x); return x; }
; #define x (arg_in(0))
;     ...
;     const float4 g0 = *(const float4*)(gsub + ch * 8), g1 = *(const float4*)(gsub + ch * 8 + 4);
; #pragma unroll
;     for (int i = 0; i < 4; ++i) { const int row = i * 8 + (lane >> 3);
;         const float4 a = *(const float4*)(stg + row * 64 + ch * 8), c = *(const float4*)(stg + row * 64 + ch * 8 + 4);
;         float ss = a.x * a.x + a.y * a.y + a.z * a.z + a.w * a.w + c.x * c.x + c.y * c.y + c.z * c.z + c.w * c.w;
;         ss = sum8f(ss);
;         const float rn = rsqrtf(ss * (1.f / 64.f) + EPS) * oscale;
;         u32x4 w; w.x = cvtpk_s(a.x * rn * g0.x, a.y * rn * g0.y); w.y = cvtpk_s(a.z * rn * g0.z, a.w * rn * g0.w); w.z = cvtpk_s(c.x * rn * g1.x, c.y * rn * g1.y); w.w = cvtpk_s(c.z * rn * g1.z, c.w * rn * g1.w);
;         *(u32x4*)(Ow + (long)row * D + ch * 8) = w; }
	v_pk_mul_f32 v[38:39], v[8:9], v[8:9]
	v_mov_b32_e32 v32, v41
	v_pk_add_f32 v[34:35], v[34:35], v[42:43]
	v_mov_b32_e32 v40, v38
	v_mov_b32_e32 v41, v30
	v_pk_add_f32 v[32:33], v[34:35], v[32:33]
	v_pk_mul_f32 v[26:27], v[18:19], v[18:19]
	v_pk_mul_f32 v[36:37], v[10:11], v[10:11]
	v_mov_b32_e32 v30, v39
	v_pk_add_f32 v[32:33], v[32:33], v[40:41]
	v_mov_b32_e32 v38, v36
	v_mov_b32_e32 v39, v26
	v_pk_add_f32 v[30:31], v[32:33], v[30:31]
	v_mov_b32_e32 v26, v37
	v_pk_add_f32 v[30:31], v[30:31], v[38:39]
	s_addc_u32 s15, s49, s15
	v_pk_add_f32 v[26:27], v[30:31], v[26:27]
	s_add_u32 s14, s14, s72
	v_mov_b32_e32 v31, v27
	v_mov_b32_e32 v30, v26
	s_addc_u32 s15, s15, s73
	v_mov_b32_dpp v31, v31 quad_perm:[1,0,3,2] row_mask:0xf bank_mask:0xf
	v_mov_b32_dpp v30, v30 quad_perm:[1,0,3,2] row_mask:0xf bank_mask:0xf
	v_pk_add_f32 v[26:27], v[26:27], v[30:31]
	v_lshl_add_u64 v[28:29], s[14:15], 0, v[128:129]
	v_mov_b32_e32 v31, v27
	v_mov_b32_e32 v30, v26
	v_lshlrev_b32_e32 v128, 11, v46
	v_mov_b32_dpp v31, v31 quad_perm:[2,3,0,1] row_mask:0xf bank_mask:0xf
	v_mov_b32_dpp v30, v30 quad_perm:[2,3,0,1] row_mask:0xf bank_mask:0xf
	v_pk_add_f32 v[26:27], v[26:27], v[30:31]
	v_lshl_add_u64 v[28:29], v[28:29], 0, s[38:39]
	v_mov_b32_e32 v31, v27
	v_mov_b32_e32 v30, v26
	v_or_b32_e32 v53, 24, v46
	v_mov_b32_dpp v31, v31 row_half_mirror row_mask:0xf bank_mask:0xf
	v_mov_b32_dpp v30, v30 row_half_mirror row_mask:0xf bank_mask:0xf
	v_pk_add_f32 v[26:27], v[26:27], v[30:31]
	s_nop 0
	v_pk_fma_f32 v[26:27], v[26:27], s[8:9], v[24:25] op_sel_hi:[1,0,0]
	s_nop 0
	v_mul_f32_e32 v30, 0x4b800000, v27
	v_cmp_gt_f32_e32 vcc, s57, v27
	v_mul_f32_e32 v34, 0x4b800000, v26
	s_nop 0
	v_cndmask_b32_e32 v27, v27, v30, vcc
	v_rsq_f32_e32 v27, v27
	v_lshl_add_u64 v[30:31], v[28:29], 0, v[128:129]
	v_lshlrev_b32_e32 v128, 11, v47
	v_mul_f32_e32 v32, 0x45800000, v27
	v_cndmask_b32_e32 v27, v27, v32, vcc
	v_mul_f32_e32 v32, v165, v27
	v_pk_mul_f32 v[20:21], v[20:21], v[32:33] op_sel_hi:[1,0]
	v_pk_mul_f32 v[22:23], v[22:23], v[32:33] op_sel_hi:[1,0]
	v_pk_mul_f32 v[16:17], v[16:17], v[32:33] op_sel_hi:[1,0]
	v_pk_mul_f32 v[32:33], v[18:19], v[32:33] op_sel_hi:[1,0]
	v_cmp_gt_f32_e32 vcc, s57, v26
	s_waitcnt vmcnt(1)
	v_pk_mul_f32 v[18:19], v[100:101], v[20:21]
	v_pk_mul_f32 v[20:21], v[102:103], v[22:23]
	s_waitcnt vmcnt(0)
	v_pk_mul_f32 v[22:23], v[104:105], v[16:17]
	v_cvt_pk_bf16_f32 v16, v18, v19
	v_cndmask_b32_e32 v19, v26, v34, vcc
	v_cvt_pk_bf16_f32 v18, v22, v23
	v_rsq_f32_e32 v22, v19
	v_cvt_pk_bf16_f32 v17, v20, v21
	v_pk_mul_f32 v[20:21], v[106:107], v[32:33]
	v_lshl_add_u64 v[26:27], v[28:29], 0, v[128:129]
	v_cvt_pk_bf16_f32 v19, v20, v21
	global_store_dwordx4 v[30:31], v[16:19], off
	v_lshl_add_u32 v30, v53, 8, v48
	v_lshlrev_b32_e32 v128, 11, v52
	v_mul_f32_e32 v16, 0x45800000, v22
	v_cndmask_b32_e32 v16, v22, v16, vcc
	v_mul_f32_e32 v16, v165, v16
	v_pk_mul_f32 v[12:13], v[12:13], v[16:17] op_sel_hi:[1,0]
	v_pk_mul_f32 v[14:15], v[14:15], v[16:17] op_sel_hi:[1,0]
	v_pk_mul_f32 v[8:9], v[8:9], v[16:17] op_sel_hi:[1,0]
	v_pk_mul_f32 v[12:13], v[100:101], v[12:13]
	v_pk_mul_f32 v[14:15], v[102:103], v[14:15]
	v_pk_mul_f32 v[8:9], v[104:105], v[8:9]
	v_cvt_pk_bf16_f32 v12, v12, v13
	v_cvt_pk_bf16_f32 v13, v14, v15
	v_cvt_pk_bf16_f32 v14, v8, v9
	v_pk_mul_f32 v[8:9], v[10:11], v[16:17] op_sel_hi:[1,0]
	v_lshl_add_u32 v16, v52, 8, v48
	v_pk_mul_f32 v[8:9], v[106:107], v[8:9]
	s_nop 0
	v_cvt_pk_bf16_f32 v15, v8, v9
	ds_read_b128 v[8:11], v16
	ds_read_b128 v[16:19], v16 offset:16
	ds_read_b128 v[20:23], v30
	ds_read_b128 v[30:33], v30 offset:16
	global_store_dwordx4 v[26:27], v[12:15], off
	s_waitcnt lgkmcnt(3)
; __device__ __forceinline__ unsigned cvtpk_s(float lo, float hi) { f32x2_t v = {lo, hi}; bf16x2_t b = __builtin_convertvector(v, bf16x2_t); return __builtin_bit_cast(unsigned, b); }
; __device__ __forceinline__ float sum8f(float x) { x += dppf<0xB1>(x); x += dppf<0x4E>(x); x += dppf<0x141>(x); return x; }
; #define x (arg_in(0))
;     ...
;     for (int i = 0; i < 4; ++i) { const int row = i * 8 + (lane >> 3);
;         const float4 a = *(const float4*)(stg + row * 64 + ch * 8), c = *(const float4*)(stg + row * 64 + ch * 8 + 4);
;         float ss = a.x * a.x + a.y * a.y + a.z * a.z + a.w * a.w + c.x * c.x + c.y * c.y + c.z * c.z + c.w * c.w;
;         ss = sum8f(ss);
;         const float rn = rsqrtf(ss * (1.f / 64.f) + EPS) * oscale;
;         u32x4 w; w.x = cvtpk_s(a.x * rn * g0.x, a.y * rn * g0.y); w.y = cvtpk_s(a.z * rn * g0.z, a.w * rn * g0.w); w.z = cvtpk_s(c.x * rn * g1.x, c.y * rn * g1.y); w.w = cvtpk_s(c.z * rn * g1.z, c.w * rn * g1.w);
;         *(u32x4*)(Ow + (long)row * D + ch * 8) = w; }
;     asm volatile("s_waitcnt lgkmcnt(0)" ::: "memory");
	v_pk_mul_f32 v[40:41], v[8:9], v[8:9]
	s_waitcnt lgkmcnt(1)
	v_pk_mul_f32 v[48:49], v[20:21], v[20:21]
	v_pk_mul_f32 v[38:39], v[10:11], v[10:11]
	v_pk_mul_f32 v[46:47], v[22:23], v[22:23]
	v_mov_b32_e32 v50, v48
	v_mov_b32_e32 v51, v40
	v_mov_b32_e32 v40, v49
	v_pk_add_f32 v[40:41], v[50:51], v[40:41]
	v_mov_b32_e32 v48, v46
	v_mov_b32_e32 v49, v38
	v_pk_mul_f32 v[36:37], v[16:17], v[16:17]
	s_waitcnt lgkmcnt(0)
	v_pk_mul_f32 v[44:45], v[30:31], v[30:31]
	v_pk_add_f32 v[40:41], v[40:41], v[48:49]
	v_mov_b32_e32 v38, v47
	v_pk_add_f32 v[38:39], v[40:41], v[38:39]
	v_mov_b32_e32 v40, v44
	v_mov_b32_e32 v41, v36
	v_pk_mul_f32 v[34:35], v[18:19], v[18:19]
	v_pk_mul_f32 v[42:43], v[32:33], v[32:33]
	v_pk_add_f32 v[38:39], v[38:39], v[40:41]
	v_mov_b32_e32 v36, v45
	v_pk_add_f32 v[36:37], v[38:39], v[36:37]
	v_mov_b32_e32 v38, v42
	v_mov_b32_e32 v39, v34
	v_pk_add_f32 v[36:37], v[36:37], v[38:39]
	v_mov_b32_e32 v34, v43
	v_pk_add_f32 v[34:35], v[36:37], v[34:35]
	v_lshl_add_u64 v[12:13], v[28:29], 0, v[128:129]
	v_mov_b32_e32 v37, v35
	v_mov_b32_e32 v36, v34
	v_lshlrev_b32_e32 v128, 11, v53
	v_mov_b32_dpp v37, v37 quad_perm:[1,0,3,2] row_mask:0xf bank_mask:0xf
	v_mov_b32_dpp v36, v36 quad_perm:[1,0,3,2] row_mask:0xf bank_mask:0xf
	v_pk_add_f32 v[34:35], v[34:35], v[36:37]
	s_nop 0
	v_mov_b32_e32 v37, v35
	v_mov_b32_e32 v36, v34
	s_nop 0
	v_mov_b32_dpp v37, v37 quad_perm:[2,3,0,1] row_mask:0xf bank_mask:0xf
	v_mov_b32_dpp v36, v36 quad_perm:[2,3,0,1] row_mask:0xf bank_mask:0xf
	v_pk_add_f32 v[34:35], v[34:35], v[36:37]
	s_nop 0
	v_mov_b32_e32 v37, v35
	v_mov_b32_e32 v36, v34
	s_nop 0
	v_mov_b32_dpp v37, v37 row_half_mirror row_mask:0xf bank_mask:0xf
	v_mov_b32_dpp v36, v36 row_half_mirror row_mask:0xf bank_mask:0xf
	v_pk_add_f32 v[34:35], v[34:35], v[36:37]
	s_nop 0
	v_pk_fma_f32 v[24:25], v[34:35], s[8:9], v[24:25] op_sel_hi:[1,0,0]
	s_nop 0
	v_mul_f32_e32 v34, 0x4b800000, v25
	v_cmp_gt_f32_e32 vcc, s57, v25
	s_nop 1
	v_cndmask_b32_e32 v25, v25, v34, vcc
	v_rsq_f32_e32 v25, v25
	s_nop 0
	v_mul_f32_e32 v14, 0x45800000, v25
	v_cndmask_b32_e32 v14, v25, v14, vcc
	v_mul_f32_e32 v14, v165, v14
	v_pk_mul_f32 v[8:9], v[8:9], v[14:15] op_sel_hi:[1,0]
	v_pk_mul_f32 v[10:11], v[10:11], v[14:15] op_sel_hi:[1,0]
	v_pk_mul_f32 v[8:9], v[100:101], v[8:9]
	v_pk_mul_f32 v[10:11], v[102:103], v[10:11]
	v_cvt_pk_bf16_f32 v8, v8, v9
	v_cvt_pk_bf16_f32 v9, v10, v11
	v_pk_mul_f32 v[10:11], v[16:17], v[14:15] op_sel_hi:[1,0]
	v_cmp_gt_f32_e32 vcc, s57, v24
	v_pk_mul_f32 v[10:11], v[104:105], v[10:11]
	v_pk_mul_f32 v[14:15], v[18:19], v[14:15] op_sel_hi:[1,0]
	v_cvt_pk_bf16_f32 v10, v10, v11
	v_mul_f32_e32 v11, 0x4b800000, v24
	v_cndmask_b32_e32 v11, v24, v11, vcc
	v_rsq_f32_e32 v16, v11
	v_pk_mul_f32 v[14:15], v[106:107], v[14:15]
	s_nop 0
	v_cvt_pk_bf16_f32 v11, v14, v15
	global_store_dwordx4 v[12:13], v[8:11], off
	s_nop 1
	v_mul_f32_e32 v8, 0x45800000, v16
	v_cndmask_b32_e32 v8, v16, v8, vcc
	v_mul_f32_e32 v8, v165, v8
	v_pk_mul_f32 v[10:11], v[20:21], v[8:9] op_sel_hi:[1,0]
	s_nop 0
	v_pk_mul_f32 v[4:5], v[100:101], v[10:11]
	v_pk_mul_f32 v[10:11], v[22:23], v[8:9] op_sel_hi:[1,0]
	v_cvt_pk_bf16_f32 v4, v4, v5
	v_pk_mul_f32 v[6:7], v[102:103], v[10:11]
	s_nop 0
	v_cvt_pk_bf16_f32 v5, v6, v7
	v_pk_mul_f32 v[6:7], v[30:31], v[8:9] op_sel_hi:[1,0]
	s_nop 0
	v_pk_mul_f32 v[0:1], v[104:105], v[6:7]
	s_nop 0
	v_cvt_pk_bf16_f32 v6, v0, v1
	v_pk_mul_f32 v[0:1], v[32:33], v[8:9] op_sel_hi:[1,0]
	s_nop 0
	v_pk_mul_f32 v[0:1], v[106:107], v[0:1]
	s_nop 0
	v_cvt_pk_bf16_f32 v7, v0, v1
	v_lshl_add_u64 v[0:1], v[28:29], 0, v[128:129]
	global_store_dwordx4 v[0:1], v[4:7], off
	s_waitcnt lgkmcnt(0)
